# v10 + P3 epilogue: all eight SSQ row loads issued up front (one wait instead of eight)
# speedup vs baseline: 1.0033x; 1.0033x over previous
; DI float fexp2(float x) { return __builtin_amdgcn_exp2f(x); }
;     DI void operator()(const AccT& acc, const Unit& u, int wv) const {
;     ...
;         const int rbase = u.pm * 256 + wr * 64 + fr;
;         float frq[8];
; #pragma unroll
;         for (int e = 0; e < 8; ++e) frq[e] = fexp2(-(float)(8 * (fq & 1) + e) * (LOG2_THETA / 16.f)) * INV2PI;
; #pragma unroll
;         for (int ai = 0; ai < 2; ++ai)
; #pragma unroll
;             for (int m = 0; m < 4; ++m) {
;                 const int row = rbase + ai * 128 + m * 16, pos = row & 2047;
;                 const f32x4 s0 = *(const f32x4*)(SSQ + (size_t)row * 8), s1 = *(const f32x4*)(SSQ + (size_t)row * 8 + 4);
;                 const float rq = __builtin_amdgcn_rsqf((s0[0] + s0[1] + s0[2] + s0[3]) * (1.f / 256.f) + EPS);
;                 const float rkv = __builtin_amdgcn_rsqf((s1[0] + s1[1] + s1[2] + s1[3]) * (1.f / 128.f) + EPS);
; #pragma unroll
;                 for (int bj = 0; bj < 2; ++bj) {
;                     const int G = 8 * u.pn + 4 * bj + wc;
;                     float v[8];
; #pragma unroll
;                     for (int e = 0; e < 4; ++e) { v[e] = acc[ai][bj][m][0][e]; v[4 + e] = acc[ai][bj][m][1][e]; }
;                     if (G < 8) {
;                         const float sc = rq * QS96;
; #pragma unroll
;                         for (int e = 0; e < 8; ++e) v[e] *= sc;
;                         *(u32x4*)(QA + ((size_t)row * 4 + (G >> 1)) * 96 + 32 * (G & 1) + 8 * fq) = pack8(v);
;                     } else if (G < 12) {
;                         const float sc = rq * QS96, Pf = (float)pos;
; #pragma unroll
;                         for (int e = 0; e < 8; ++e) { const float a = v[e] * sc, b = shx(a, 32); float c, s; sincos_rev(Pf * frq[e], c, s); v[e] = (fq < 2) ? (a * c - b * s) : (b * s + a * c); }
;                         *(u32x4*)(QA + ((size_t)row * 4 + (G - 8)) * 96 + 64 + 8 * fq) = pack8(v);
;                     } else if (G < 20) {
;                         const int Gp = G - 12;
; #pragma unroll
;                         for (int e = 0; e < 8; ++e) v[e] *= rkv;
;                         *(u32x4*)(KA + ((size_t)row * 4 + (Gp >> 1)) * 96 + 32 * (Gp & 1) + 8 * fq) = pack8(v);
;                     } else if (G < 28) {
;                         const int Gp = G - 20;
; #pragma unroll
;                         for (int e = 0; e < 8; ++e) v[e] *= rkv;
.LBB0_931:
	s_mov_b32 s4, s33
	v_mov_b32_e32 v128, v145
	s_lshl_b32 s6, s4, 4
	v_mbcnt_lo_u32_b32 v128, -1, v128
	v_mbcnt_hi_u32_b32 v128, -1, v128
	v_ashrrev_i32_e32 v129, 4, v128
	v_lshlrev_b32_e32 v138, 3, v129
	v_and_b32_e32 v130, 8, v138
	v_cvt_f32_ubyte0_e32 v131, v130
	v_mul_f32_e32 v131, 0xbf549a78, v131
	v_exp_f32_e32 v131, v131
	s_lshl_b32 s5, s11, 8
	s_andn2_b32 s6, s6, 63
	s_add_i32 s6, s6, s5
	v_mul_f32_e32 v161, 0.15915494, v131
	v_or_b32_e32 v131, 1, v130
	v_cvt_f32_ubyte0_e32 v131, v131
	v_mul_f32_e32 v131, 0xbf549a78, v131
	v_exp_f32_e32 v131, v131
	v_and_b32_e32 v128, 15, v128
	s_and_b32 s11, s4, 3
	v_or_b32_e32 v140, s6, v128
	v_mul_f32_e32 v160, 0.15915494, v131
	v_or_b32_e32 v131, 2, v130
	v_cvt_f32_ubyte0_e32 v131, v131
	v_mul_f32_e32 v131, 0xbf549a78, v131
	v_exp_f32_e32 v131, v131
	s_lshl_b32 s4, s4, 5
	s_and_b32 s90, s4, 32
	v_cmp_gt_i32_e64 s[4:5], 2, v129
	v_mul_f32_e32 v159, 0.15915494, v131
	v_or_b32_e32 v131, 3, v130
	v_cvt_f32_ubyte0_e32 v131, v131
	v_mul_f32_e32 v131, 0xbf549a78, v131
	v_exp_f32_e32 v131, v131
	v_mov_b32_e32 v129, s6
	s_movk_i32 s6, 0x7cf
	v_ashrrev_i32_e32 v141, 31, v140
	v_mul_f32_e32 v158, 0.15915494, v131
	v_or_b32_e32 v131, 4, v130
	v_cvt_f32_ubyte0_e32 v131, v131
	v_mul_f32_e32 v131, 0xbf549a78, v131
	v_exp_f32_e32 v131, v131
	v_bitop3_b32 v139, v128, s6, v129 bitop3:0xc8
	v_lshlrev_b64 v[128:129], 5, v[140:141]
	v_lshl_add_u64 v[142:143], s[18:19], 0, v[128:129]
	v_mul_f32_e32 v157, 0.15915494, v131
	v_or_b32_e32 v131, 5, v130
	v_cvt_f32_ubyte0_e32 v131, v131
	v_mul_f32_e32 v131, 0xbf549a78, v131
	v_exp_f32_e32 v131, v131
	s_lshl_b32 s35, s10, 3
	s_or_b32 s91, s11, s35
	s_cmp_gt_i32 s91, 7
	v_mul_f32_e32 v156, 0.15915494, v131
	v_or_b32_e32 v131, 6, v130
	v_or_b32_e32 v130, 7, v130
	v_cvt_f32_ubyte0_e32 v131, v131
	v_cvt_f32_ubyte0_e32 v130, v130
	v_mul_f32_e32 v131, 0xbf549a78, v131
	v_mul_f32_e32 v130, 0xbf549a78, v130
	v_exp_f32_e32 v131, v131
	v_exp_f32_e32 v130, v130
	s_cselect_b64 s[8:9], -1, 0
	s_and_b64 vcc, exec, s[8:9]
	v_mul_f32_e32 v155, 0.15915494, v131
	v_mul_f32_e32 v154, 0.15915494, v130
	flat_load_dwordx4 v[128:131], v[142:143]
	flat_load_dwordx4 v[150:153], v[142:143] offset:16
	global_load_dwordx4 v[204:207], v[142:143], off offset:512
	global_load_dwordx4 v[208:211], v[142:143], off offset:528
	global_load_dwordx4 v[212:215], v[142:143], off offset:1024
	global_load_dwordx4 v[216:219], v[142:143], off offset:1040
	global_load_dwordx4 v[220:223], v[142:143], off offset:1536
	global_load_dwordx4 v[224:227], v[142:143], off offset:1552
	v_mov_b32_e32 v194, 0x1000
	v_mov_b32_e32 v195, 0
	v_lshl_add_u64 v[194:195], v[142:143], 0, v[194:195]
	global_load_dwordx4 v[228:231], v[194:195], off
	global_load_dwordx4 v[232:235], v[194:195], off offset:16
	global_load_dwordx4 v[236:239], v[194:195], off offset:512
	global_load_dwordx4 v[240:243], v[194:195], off offset:528
	global_load_dwordx4 v[244:247], v[194:195], off offset:1024
	global_load_dwordx4 v[248:251], v[194:195], off offset:1040
	global_load_dwordx4 v[186:189], v[194:195], off offset:1536
	global_load_dwordx4 v[190:193], v[194:195], off offset:1552
	v_lshlrev_b64 v[142:143], 2, v[140:141]
	s_waitcnt vmcnt(0) lgkmcnt(0)
	v_add_f32_e32 v128, v128, v129
	v_add_f32_e32 v128, v130, v128
	v_add_f32_e32 v129, v150, v151
	v_add_f32_e32 v128, v131, v128
	v_add_f32_e32 v129, v152, v129
	v_fmamk_f32 v128, v128, 0x3b800000, v179
	v_add_f32_e32 v129, v153, v129
	v_rsq_f32_e32 v128, v128
	v_fmamk_f32 v129, v129, 0x3c000000, v179
	v_rsq_f32_e32 v148, v129
	v_lshlrev_b64 v[150:151], 9, v[140:141]
	v_cvt_f32_u32_e32 v141, v139
	v_mul_f32_e32 v146, 0x3e16c740, v128
	s_cbranch_vccz .LBB0_936
	s_cmp_gt_u32 s35, 11
	s_cbranch_scc0 .LBB0_937
	s_cmp_gt_u32 s35, 19
	s_cbranch_scc0 .LBB0_938
	s_mov_b64 s[26:27], 0
	s_cmp_lt_u32 s35, 28
	s_mov_b64 s[6:7], 0
	s_cbranch_scc0 .LBB0_939
	s_sub_i32 s6, s91, 20
	v_pk_mul_f32 v[128:129], v[124:125], v[148:149] op_sel_hi:[1,0]
	v_pk_mul_f32 v[130:131], v[126:127], v[148:149] op_sel_hi:[1,0]
	v_pk_mul_f32 v[152:153], v[120:121], v[148:149] op_sel_hi:[1,0]
	s_lshr_b32 s68, s6, 1
	v_cvt_pk_bf16_f32 v128, v128, v129
	v_cvt_pk_bf16_f32 v129, v130, v131
	v_cvt_pk_bf16_f32 v130, v152, v153
	v_lshl_add_u64 v[152:153], s[16:17], 0, v[150:151]
	s_lshl_b64 s[6:7], s[68:69], 7
	v_pk_mul_f32 v[162:163], v[122:123], v[148:149] op_sel_hi:[1,0]
	v_lshl_add_u64 v[152:153], v[152:153], 0, s[6:7]
	s_lshl_b32 s68, s90, 1
	v_cvt_pk_bf16_f32 v131, v162, v163
	v_lshl_add_u64 v[152:153], v[152:153], 0, s[68:69]
	s_mov_b64 s[6:7], -1
	s_branch .LBB0_939

;     DI void operator()(const AccT& acc, const Unit& u, int wv) const {
;     ...
;                 const int row = rbase + ai * 128 + m * 16, pos = row & 2047;
;                 const f32x4 s0 = *(const f32x4*)(SSQ + (size_t)row * 8), s1 = *(const f32x4*)(SSQ + (size_t)row * 8 + 4);
;                 const float rq = __builtin_amdgcn_rsqf((s0[0] + s0[1] + s0[2] + s0[3]) * (1.f / 256.f) + EPS);
;                 const float rkv = __builtin_amdgcn_rsqf((s1[0] + s1[1] + s1[2] + s1[3]) * (1.f / 128.f) + EPS);
.LBB0_963:
	v_or_b32_e32 v124, 16, v140
	v_ashrrev_i32_e32 v125, 31, v124
	v_lshlrev_b64 v[112:113], 5, v[124:125]
	v_lshl_add_u64 v[116:117], s[18:19], 0, v[112:113]
	v_mov_b32_e32 v112, v204
	v_mov_b32_e32 v113, v205
	v_mov_b32_e32 v114, v206
	v_mov_b32_e32 v115, v207
	s_nop 0
	v_mov_b32_e32 v116, v208
	v_mov_b32_e32 v117, v209
	v_mov_b32_e32 v118, v210
	v_mov_b32_e32 v119, v211
	s_movk_i32 s6, 0x7df
	v_bitop3_b32 v121, v140, s6, 16 bitop3:0xc8
	v_lshlrev_b64 v[122:123], 9, v[124:125]
	s_andn2_b64 vcc, exec, s[8:9]
	v_add_f32_e32 v112, v112, v113
	v_add_f32_e32 v112, v114, v112
	v_add_f32_e32 v112, v115, v112
	v_add_f32_e32 v113, v116, v117
	v_fmamk_f32 v112, v112, 0x3b800000, v179
	v_add_f32_e32 v113, v118, v113
	v_rsq_f32_e32 v112, v112
	v_add_f32_e32 v113, v119, v113
	v_fmamk_f32 v113, v113, 0x3c000000, v179
	v_rsq_f32_e32 v120, v113
	v_cvt_f32_u32_e32 v119, v121
	v_mul_f32_e32 v118, 0x3e16c740, v112
	v_cndmask_b32_e64 v112, 0, 1, s[8:9]
	v_lshlrev_b64 v[116:117], 2, v[124:125]
	v_cmp_ne_u32_e64 s[6:7], 1, v112
	s_cbranch_vccnz .LBB0_968
	s_cmp_gt_u32 s35, 11
	s_cbranch_scc0 .LBB0_969
	s_cmp_gt_u32 s35, 19
	s_cbranch_scc0 .LBB0_970
	s_mov_b64 s[28:29], 0
	s_cmp_lt_u32 s35, 28
	s_mov_b64 s[8:9], 0
	s_cbranch_scc0 .LBB0_971
	s_sub_i32 s8, s91, 20
	v_pk_mul_f32 v[112:113], v[108:109], v[120:121] op_sel_hi:[1,0]
	v_pk_mul_f32 v[114:115], v[110:111], v[120:121] op_sel_hi:[1,0]
	v_pk_mul_f32 v[124:125], v[104:105], v[120:121] op_sel_hi:[1,0]
	s_lshr_b32 s68, s8, 1
	v_cvt_pk_bf16_f32 v112, v112, v113
	v_cvt_pk_bf16_f32 v113, v114, v115
	v_cvt_pk_bf16_f32 v114, v124, v125
	v_lshl_add_u64 v[124:125], s[16:17], 0, v[122:123]
	s_lshl_b64 s[8:9], s[68:69], 7
	v_pk_mul_f32 v[126:127], v[106:107], v[120:121] op_sel_hi:[1,0]
	v_lshl_add_u64 v[124:125], v[124:125], 0, s[8:9]
	s_lshl_b32 s68, s90, 1
	v_cvt_pk_bf16_f32 v115, v126, v127
	v_lshl_add_u64 v[124:125], v[124:125], 0, s[68:69]
	s_mov_b64 s[8:9], -1
	s_branch .LBB0_971

;     DI void operator()(const AccT& acc, const Unit& u, int wv) const {
;     ...
;                 const int row = rbase + ai * 128 + m * 16, pos = row & 2047;
;                 const f32x4 s0 = *(const f32x4*)(SSQ + (size_t)row * 8), s1 = *(const f32x4*)(SSQ + (size_t)row * 8 + 4);
;                 const float rq = __builtin_amdgcn_rsqf((s0[0] + s0[1] + s0[2] + s0[3]) * (1.f / 256.f) + EPS);
;                 const float rkv = __builtin_amdgcn_rsqf((s1[0] + s1[1] + s1[2] + s1[3]) * (1.f / 128.f) + EPS);
.LBB0_995:
	v_or_b32_e32 v108, 32, v140
	v_ashrrev_i32_e32 v109, 31, v108
	v_lshlrev_b64 v[96:97], 5, v[108:109]
	v_lshl_add_u64 v[100:101], s[18:19], 0, v[96:97]
	v_mov_b32_e32 v96, v212
	v_mov_b32_e32 v97, v213
	v_mov_b32_e32 v98, v214
	v_mov_b32_e32 v99, v215
	s_nop 0
	v_mov_b32_e32 v100, v216
	v_mov_b32_e32 v101, v217
	v_mov_b32_e32 v102, v218
	v_mov_b32_e32 v103, v219
	s_movk_i32 s11, 0x7ef
	v_bitop3_b32 v105, v140, s11, 32 bitop3:0xc8
	v_lshlrev_b64 v[106:107], 9, v[108:109]
	s_and_b64 vcc, exec, s[6:7]
	v_add_f32_e32 v96, v96, v97
	v_add_f32_e32 v97, v100, v101
	v_add_f32_e32 v96, v98, v96
	v_add_f32_e32 v97, v102, v97
	v_add_f32_e32 v96, v99, v96
	v_add_f32_e32 v97, v103, v97
	v_fmamk_f32 v96, v96, 0x3b800000, v179
	v_fmamk_f32 v97, v97, 0x3c000000, v179
	v_rsq_f32_e32 v96, v96
	v_rsq_f32_e32 v104, v97
	v_cvt_f32_u32_e32 v103, v105
	v_lshlrev_b64 v[100:101], 2, v[108:109]
	v_mul_f32_e32 v102, 0x3e16c740, v96
	s_cbranch_vccnz .LBB0_1000
	s_cmp_gt_u32 s35, 11
	s_cbranch_scc0 .LBB0_1001
	s_cmp_gt_u32 s35, 19
	s_cbranch_scc0 .LBB0_1002
	s_mov_b64 s[28:29], 0
	s_cmp_lt_u32 s35, 28
	s_mov_b64 s[26:27], 0
	s_cbranch_scc0 .LBB0_1003
	s_sub_i32 s11, s91, 20
	v_pk_mul_f32 v[96:97], v[92:93], v[104:105] op_sel_hi:[1,0]
	v_pk_mul_f32 v[98:99], v[94:95], v[104:105] op_sel_hi:[1,0]
	v_pk_mul_f32 v[108:109], v[88:89], v[104:105] op_sel_hi:[1,0]
	s_lshr_b32 s68, s11, 1
	v_cvt_pk_bf16_f32 v96, v96, v97
	v_cvt_pk_bf16_f32 v97, v98, v99
	v_cvt_pk_bf16_f32 v98, v108, v109
	v_lshl_add_u64 v[108:109], s[16:17], 0, v[106:107]
	s_lshl_b64 s[26:27], s[68:69], 7
	v_pk_mul_f32 v[110:111], v[90:91], v[104:105] op_sel_hi:[1,0]
	v_lshl_add_u64 v[108:109], v[108:109], 0, s[26:27]
	s_lshl_b32 s68, s90, 1
	v_cvt_pk_bf16_f32 v99, v110, v111
	v_lshl_add_u64 v[108:109], v[108:109], 0, s[68:69]
	s_mov_b64 s[26:27], -1
	s_branch .LBB0_1003

;     DI void operator()(const AccT& acc, const Unit& u, int wv) const {
;     ...
;                 const int row = rbase + ai * 128 + m * 16, pos = row & 2047;
;                 const f32x4 s0 = *(const f32x4*)(SSQ + (size_t)row * 8), s1 = *(const f32x4*)(SSQ + (size_t)row * 8 + 4);
;                 const float rq = __builtin_amdgcn_rsqf((s0[0] + s0[1] + s0[2] + s0[3]) * (1.f / 256.f) + EPS);
;                 const float rkv = __builtin_amdgcn_rsqf((s1[0] + s1[1] + s1[2] + s1[3]) * (1.f / 128.f) + EPS);
.LBB0_1027:
	v_or_b32_e32 v92, 48, v140
	v_ashrrev_i32_e32 v93, 31, v92
	v_lshlrev_b64 v[80:81], 5, v[92:93]
	v_lshl_add_u64 v[84:85], s[18:19], 0, v[80:81]
	v_mov_b32_e32 v80, v220
	v_mov_b32_e32 v81, v221
	v_mov_b32_e32 v82, v222
	v_mov_b32_e32 v83, v223
	s_nop 0
	v_mov_b32_e32 v84, v224
	v_mov_b32_e32 v85, v225
	v_mov_b32_e32 v86, v226
	v_mov_b32_e32 v87, v227
	s_movk_i32 s11, 0x7ff
	v_bitop3_b32 v89, v140, s11, 48 bitop3:0xc8
	v_lshlrev_b64 v[90:91], 9, v[92:93]
	s_and_b64 vcc, exec, s[6:7]
	v_add_f32_e32 v80, v80, v81
	v_add_f32_e32 v81, v84, v85
	v_add_f32_e32 v80, v82, v80
	v_add_f32_e32 v81, v86, v81
	v_add_f32_e32 v80, v83, v80
	v_add_f32_e32 v81, v87, v81
	v_fmamk_f32 v80, v80, 0x3b800000, v179
	v_fmamk_f32 v81, v81, 0x3c000000, v179
	v_rsq_f32_e32 v80, v80
	v_rsq_f32_e32 v88, v81
	v_cvt_f32_u32_e32 v87, v89
	v_lshlrev_b64 v[84:85], 2, v[92:93]
	v_mul_f32_e32 v86, 0x3e16c740, v80
	s_cbranch_vccnz .LBB0_1032
	s_cmp_gt_u32 s35, 11
	s_cbranch_scc0 .LBB0_1033
	s_cmp_gt_u32 s35, 19
	s_cbranch_scc0 .LBB0_1034
	s_mov_b64 s[28:29], 0
	s_cmp_lt_u32 s35, 28
	s_mov_b64 s[26:27], 0
	s_cbranch_scc0 .LBB0_1035
	s_sub_i32 s11, s91, 20
	v_pk_mul_f32 v[80:81], v[76:77], v[88:89] op_sel_hi:[1,0]
	v_pk_mul_f32 v[82:83], v[78:79], v[88:89] op_sel_hi:[1,0]
	v_pk_mul_f32 v[92:93], v[72:73], v[88:89] op_sel_hi:[1,0]
	s_lshr_b32 s68, s11, 1
	v_cvt_pk_bf16_f32 v80, v80, v81
	v_cvt_pk_bf16_f32 v81, v82, v83
	v_cvt_pk_bf16_f32 v82, v92, v93
	v_lshl_add_u64 v[92:93], s[16:17], 0, v[90:91]
	s_lshl_b64 s[26:27], s[68:69], 7
	v_pk_mul_f32 v[94:95], v[74:75], v[88:89] op_sel_hi:[1,0]
	v_lshl_add_u64 v[92:93], v[92:93], 0, s[26:27]
	s_lshl_b32 s68, s90, 1
	v_cvt_pk_bf16_f32 v83, v94, v95
	v_lshl_add_u64 v[92:93], v[92:93], 0, s[68:69]
	s_mov_b64 s[26:27], -1
	s_branch .LBB0_1035

;     DI void operator()(const AccT& acc, const Unit& u, int wv) const {
;     ...
;                 const int row = rbase + ai * 128 + m * 16, pos = row & 2047;
;                 const f32x4 s0 = *(const f32x4*)(SSQ + (size_t)row * 8), s1 = *(const f32x4*)(SSQ + (size_t)row * 8 + 4);
;                 const float rq = __builtin_amdgcn_rsqf((s0[0] + s0[1] + s0[2] + s0[3]) * (1.f / 256.f) + EPS);
;                 const float rkv = __builtin_amdgcn_rsqf((s1[0] + s1[1] + s1[2] + s1[3]) * (1.f / 128.f) + EPS);
.LBB0_1059:
	v_add_u32_e32 v76, 0x80, v140
	v_ashrrev_i32_e32 v77, 31, v76
	v_lshlrev_b64 v[64:65], 5, v[76:77]
	v_lshl_add_u64 v[68:69], s[18:19], 0, v[64:65]
	v_mov_b32_e32 v64, v228
	v_mov_b32_e32 v65, v229
	v_mov_b32_e32 v66, v230
	v_mov_b32_e32 v67, v231
	s_nop 0
	v_mov_b32_e32 v68, v232
	v_mov_b32_e32 v69, v233
	v_mov_b32_e32 v70, v234
	v_mov_b32_e32 v71, v235
	v_and_b32_e32 v73, 0x7cf, v76
	v_lshlrev_b64 v[74:75], 9, v[76:77]
	s_and_b64 vcc, exec, s[6:7]
	v_add_f32_e32 v64, v64, v65
	v_add_f32_e32 v65, v68, v69
	v_add_f32_e32 v64, v66, v64
	v_add_f32_e32 v65, v70, v65
	v_add_f32_e32 v64, v67, v64
	v_add_f32_e32 v65, v71, v65
	v_fmamk_f32 v64, v64, 0x3b800000, v179
	v_fmamk_f32 v65, v65, 0x3c000000, v179
	v_rsq_f32_e32 v64, v64
	v_rsq_f32_e32 v72, v65
	v_cvt_f32_u32_e32 v71, v73
	v_lshlrev_b64 v[68:69], 2, v[76:77]
	v_mul_f32_e32 v70, 0x3e16c740, v64
	s_cbranch_vccnz .LBB0_1064
	s_cmp_gt_u32 s35, 11
	s_cbranch_scc0 .LBB0_1065
	s_cmp_gt_u32 s35, 19
	s_cbranch_scc0 .LBB0_1066
	s_mov_b64 s[28:29], 0
	s_cmp_lt_u32 s35, 28
	s_mov_b64 s[26:27], 0
	s_cbranch_scc0 .LBB0_1067
	s_sub_i32 s11, s91, 20
	v_pk_mul_f32 v[64:65], v[60:61], v[72:73] op_sel_hi:[1,0]
	v_pk_mul_f32 v[66:67], v[62:63], v[72:73] op_sel_hi:[1,0]
	v_pk_mul_f32 v[76:77], v[56:57], v[72:73] op_sel_hi:[1,0]
	s_lshr_b32 s68, s11, 1
	v_cvt_pk_bf16_f32 v64, v64, v65
	v_cvt_pk_bf16_f32 v65, v66, v67
	v_cvt_pk_bf16_f32 v66, v76, v77
	v_lshl_add_u64 v[76:77], s[16:17], 0, v[74:75]
	s_lshl_b64 s[26:27], s[68:69], 7
	v_pk_mul_f32 v[78:79], v[58:59], v[72:73] op_sel_hi:[1,0]
	v_lshl_add_u64 v[76:77], v[76:77], 0, s[26:27]
	s_lshl_b32 s68, s90, 1
	v_cvt_pk_bf16_f32 v67, v78, v79
	v_lshl_add_u64 v[76:77], v[76:77], 0, s[68:69]
	s_mov_b64 s[26:27], -1
	s_branch .LBB0_1067

;     DI void operator()(const AccT& acc, const Unit& u, int wv) const {
;     ...
;                 const int row = rbase + ai * 128 + m * 16, pos = row & 2047;
;                 const f32x4 s0 = *(const f32x4*)(SSQ + (size_t)row * 8), s1 = *(const f32x4*)(SSQ + (size_t)row * 8 + 4);
;                 const float rq = __builtin_amdgcn_rsqf((s0[0] + s0[1] + s0[2] + s0[3]) * (1.f / 256.f) + EPS);
;                 const float rkv = __builtin_amdgcn_rsqf((s1[0] + s1[1] + s1[2] + s1[3]) * (1.f / 128.f) + EPS);
.LBB0_1091:
	v_add_u32_e32 v60, 0x90, v140
	v_ashrrev_i32_e32 v61, 31, v60
	v_lshlrev_b64 v[48:49], 5, v[60:61]
	v_lshl_add_u64 v[52:53], s[18:19], 0, v[48:49]
	v_mov_b32_e32 v48, v236
	v_mov_b32_e32 v49, v237
	v_mov_b32_e32 v50, v238
	v_mov_b32_e32 v51, v239
	s_nop 0
	v_mov_b32_e32 v52, v240
	v_mov_b32_e32 v53, v241
	v_mov_b32_e32 v54, v242
	v_mov_b32_e32 v55, v243
	v_and_b32_e32 v57, 0x7df, v60
	v_lshlrev_b64 v[58:59], 9, v[60:61]
	s_and_b64 vcc, exec, s[6:7]
	v_add_f32_e32 v48, v48, v49
	v_add_f32_e32 v49, v52, v53
	v_add_f32_e32 v48, v50, v48
	v_add_f32_e32 v49, v54, v49
	v_add_f32_e32 v48, v51, v48
	v_add_f32_e32 v49, v55, v49
	v_fmamk_f32 v48, v48, 0x3b800000, v179
	v_fmamk_f32 v49, v49, 0x3c000000, v179
	v_rsq_f32_e32 v48, v48
	v_rsq_f32_e32 v56, v49
	v_cvt_f32_u32_e32 v55, v57
	v_lshlrev_b64 v[52:53], 2, v[60:61]
	v_mul_f32_e32 v54, 0x3e16c740, v48
	s_cbranch_vccnz .LBB0_1096
	s_cmp_gt_u32 s35, 11
	s_cbranch_scc0 .LBB0_1097
	s_cmp_gt_u32 s35, 19
	s_cbranch_scc0 .LBB0_1098
	s_mov_b64 s[28:29], 0
	s_cmp_lt_u32 s35, 28
	s_mov_b64 s[26:27], 0
	s_cbranch_scc0 .LBB0_1099
	s_sub_i32 s11, s91, 20
	v_pk_mul_f32 v[48:49], v[44:45], v[56:57] op_sel_hi:[1,0]
	v_pk_mul_f32 v[50:51], v[46:47], v[56:57] op_sel_hi:[1,0]
	v_pk_mul_f32 v[60:61], v[40:41], v[56:57] op_sel_hi:[1,0]
	s_lshr_b32 s68, s11, 1
	v_cvt_pk_bf16_f32 v48, v48, v49
	v_cvt_pk_bf16_f32 v49, v50, v51
	v_cvt_pk_bf16_f32 v50, v60, v61
	v_lshl_add_u64 v[60:61], s[16:17], 0, v[58:59]
	s_lshl_b64 s[26:27], s[68:69], 7
	v_pk_mul_f32 v[62:63], v[42:43], v[56:57] op_sel_hi:[1,0]
	v_lshl_add_u64 v[60:61], v[60:61], 0, s[26:27]
	s_lshl_b32 s68, s90, 1
	v_cvt_pk_bf16_f32 v51, v62, v63
	v_lshl_add_u64 v[60:61], v[60:61], 0, s[68:69]
	s_mov_b64 s[26:27], -1
	s_branch .LBB0_1099

;     DI void operator()(const AccT& acc, const Unit& u, int wv) const {
;     ...
;                 const int row = rbase + ai * 128 + m * 16, pos = row & 2047;
;                 const f32x4 s0 = *(const f32x4*)(SSQ + (size_t)row * 8), s1 = *(const f32x4*)(SSQ + (size_t)row * 8 + 4);
;                 const float rq = __builtin_amdgcn_rsqf((s0[0] + s0[1] + s0[2] + s0[3]) * (1.f / 256.f) + EPS);
;                 const float rkv = __builtin_amdgcn_rsqf((s1[0] + s1[1] + s1[2] + s1[3]) * (1.f / 128.f) + EPS);
.LBB0_1123:
	v_add_u32_e32 v44, 0xa0, v140
	v_ashrrev_i32_e32 v45, 31, v44
	v_lshlrev_b64 v[32:33], 5, v[44:45]
	v_lshl_add_u64 v[36:37], s[18:19], 0, v[32:33]
	v_mov_b32_e32 v32, v244
	v_mov_b32_e32 v33, v245
	v_mov_b32_e32 v34, v246
	v_mov_b32_e32 v35, v247
	s_nop 0
	v_mov_b32_e32 v36, v248
	v_mov_b32_e32 v37, v249
	v_mov_b32_e32 v38, v250
	v_mov_b32_e32 v39, v251
	v_and_b32_e32 v41, 0x7ef, v44
	v_lshlrev_b64 v[42:43], 9, v[44:45]
	s_and_b64 vcc, exec, s[6:7]
	v_add_f32_e32 v32, v32, v33
	v_add_f32_e32 v33, v36, v37
	v_add_f32_e32 v32, v34, v32
	v_add_f32_e32 v33, v38, v33
	v_add_f32_e32 v32, v35, v32
	v_add_f32_e32 v33, v39, v33
	v_fmamk_f32 v32, v32, 0x3b800000, v179
	v_fmamk_f32 v33, v33, 0x3c000000, v179
	v_rsq_f32_e32 v32, v32
	v_rsq_f32_e32 v40, v33
	v_cvt_f32_u32_e32 v39, v41
	v_lshlrev_b64 v[36:37], 2, v[44:45]
	v_mul_f32_e32 v38, 0x3e16c740, v32
	s_cbranch_vccnz .LBB0_1128
	s_cmp_gt_u32 s35, 11
	s_cbranch_scc0 .LBB0_1129
	s_cmp_gt_u32 s35, 19
	s_cbranch_scc0 .LBB0_1130
	s_mov_b64 s[28:29], 0
	s_cmp_lt_u32 s35, 28
	s_mov_b64 s[26:27], 0
	s_cbranch_scc0 .LBB0_1131
	s_sub_i32 s11, s91, 20
	v_pk_mul_f32 v[32:33], v[28:29], v[40:41] op_sel_hi:[1,0]
	v_pk_mul_f32 v[34:35], v[30:31], v[40:41] op_sel_hi:[1,0]
	v_pk_mul_f32 v[44:45], v[24:25], v[40:41] op_sel_hi:[1,0]
	s_lshr_b32 s68, s11, 1
	v_cvt_pk_bf16_f32 v32, v32, v33
	v_cvt_pk_bf16_f32 v33, v34, v35
	v_cvt_pk_bf16_f32 v34, v44, v45
	v_lshl_add_u64 v[44:45], s[16:17], 0, v[42:43]
	s_lshl_b64 s[26:27], s[68:69], 7
	v_pk_mul_f32 v[46:47], v[26:27], v[40:41] op_sel_hi:[1,0]
	v_lshl_add_u64 v[44:45], v[44:45], 0, s[26:27]
	s_lshl_b32 s68, s90, 1
	v_cvt_pk_bf16_f32 v35, v46, v47
	v_lshl_add_u64 v[44:45], v[44:45], 0, s[68:69]
	s_mov_b64 s[26:27], -1
	s_branch .LBB0_1131

;     DI void operator()(const AccT& acc, const Unit& u, int wv) const {
;     ...
;                 const int row = rbase + ai * 128 + m * 16, pos = row & 2047;
;                 const f32x4 s0 = *(const f32x4*)(SSQ + (size_t)row * 8), s1 = *(const f32x4*)(SSQ + (size_t)row * 8 + 4);
;                 const float rq = __builtin_amdgcn_rsqf((s0[0] + s0[1] + s0[2] + s0[3]) * (1.f / 256.f) + EPS);
;                 const float rkv = __builtin_amdgcn_rsqf((s1[0] + s1[1] + s1[2] + s1[3]) * (1.f / 128.f) + EPS);
.LBB0_1155:
	v_add_u32_e32 v28, 0xb0, v140
	v_ashrrev_i32_e32 v29, 31, v28
	v_lshlrev_b64 v[16:17], 5, v[28:29]
	v_lshl_add_u64 v[20:21], s[18:19], 0, v[16:17]
	v_mov_b32_e32 v16, v186
	v_mov_b32_e32 v17, v187
	v_mov_b32_e32 v18, v188
	v_mov_b32_e32 v19, v189
	s_nop 0
	v_mov_b32_e32 v20, v190
	v_mov_b32_e32 v21, v191
	v_mov_b32_e32 v22, v192
	v_mov_b32_e32 v23, v193
	v_and_b32_e32 v25, 0x7ff, v28
	v_lshlrev_b64 v[26:27], 9, v[28:29]
	s_and_b64 vcc, exec, s[6:7]
	v_add_f32_e32 v16, v16, v17
	v_add_f32_e32 v16, v18, v16
	v_add_f32_e32 v17, v20, v21
	v_add_f32_e32 v16, v19, v16
	v_add_f32_e32 v17, v22, v17
	v_fmamk_f32 v16, v16, 0x3b800000, v179
	v_add_f32_e32 v17, v23, v17
	v_rsq_f32_e32 v16, v16
	v_fmamk_f32 v17, v17, 0x3c000000, v179
	v_rsq_f32_e32 v24, v17
	v_cvt_f32_u32_e32 v23, v25
	v_lshlrev_b64 v[20:21], 2, v[28:29]
	v_mul_f32_e32 v22, 0x3e16c740, v16
	s_cbranch_vccnz .LBB0_1160
	s_cmp_gt_u32 s35, 11
	s_cbranch_scc0 .LBB0_1161
	s_cmp_gt_u32 s35, 19
	s_cbranch_scc0 .LBB0_1162
	s_mov_b64 s[26:27], 0
	s_cmp_lt_u32 s35, 28
	s_mov_b64 s[6:7], 0
	s_cbranch_scc0 .LBB0_1163
	s_sub_i32 s6, s91, 20
	v_pk_mul_f32 v[16:17], v[12:13], v[24:25] op_sel_hi:[1,0]
	v_pk_mul_f32 v[18:19], v[14:15], v[24:25] op_sel_hi:[1,0]
	v_pk_mul_f32 v[28:29], v[8:9], v[24:25] op_sel_hi:[1,0]
	s_lshr_b32 s68, s6, 1
	v_cvt_pk_bf16_f32 v16, v16, v17
	v_cvt_pk_bf16_f32 v17, v18, v19
	v_cvt_pk_bf16_f32 v18, v28, v29
	v_lshl_add_u64 v[28:29], s[16:17], 0, v[26:27]
	s_lshl_b64 s[6:7], s[68:69], 7
	v_pk_mul_f32 v[30:31], v[10:11], v[24:25] op_sel_hi:[1,0]
	v_lshl_add_u64 v[28:29], v[28:29], 0, s[6:7]
	s_lshl_b32 s68, s90, 1
	v_cvt_pk_bf16_f32 v19, v30, v31
	v_lshl_add_u64 v[28:29], v[28:29], 0, s[68:69]
	s_mov_b64 s[6:7], -1
	s_branch .LBB0_1163
